# scan fast path: chunk loads issued 24 ahead of the recurrence
# baseline (speedup 1.0000x reference)
; #define LAS __attribute__((address_space(3)))
; __global__ void __launch_bounds__(512) hymba_fwd(Args a) {
;     extern __shared__ __attribute__((aligned(16))) unsigned char lds_raw[];
;     LAS unsigned char* lds = (LAS unsigned char*)lds_raw;
;     const int G = gridDim.x, bx = blockIdx.x;
;     const int lo = a.ph_lo, hi = a.ph_hi;
;     bf16_t* proj = (bf16_t*)(a.ws + WS_PROJ);
;     ...
;     volatile LAS unsigned* xst = (volatile LAS unsigned*)(lds + LDS_BYTES - 16);
;     if (threadIdx.x < 2) xst[threadIdx.x] = 0u;
;     __syncthreads();
;     XcdBarrier xbar; xbar.bar = (unsigned*)(a.ws + WS_BAR); xbar.x = 0; xbar.st = xst;
;     if (hi - lo > 1) xbar = xcd_barrier_post((unsigned*)(a.ws + WS_BAR), xst);
_Z9hymba_fwd4Args:
	s_mov_b32 s99, 0
	s_mov_b32 s101, 0
	s_mov_b32 s100, s2
.Lprobe_reentry:
	s_load_dwordx16 s[64:79], s[0:1], 0x40
	s_load_dwordx2 s[4:5], s[0:1], 0x80
	s_load_dword s3, s[0:1], 0x90
	v_and_b32_e32 v178, 0x3ff, v0
	v_cmp_gt_u32_e32 vcc, 2, v178
	s_waitcnt lgkmcnt(0)
	v_writelane_b32 v246, s4, 0
	s_nop 1
	v_writelane_b32 v246, s5, 1
	s_add_u32 s4, s0, 0x90
	s_addc_u32 s5, s1, 0
	v_writelane_b32 v246, s4, 2
	s_nop 1
	v_writelane_b32 v246, s5, 3
	s_and_saveexec_b64 s[4:5], vcc
	v_lshl_add_u32 v1, v178, 2, 0
	v_add_u32_e32 v1, 0x23ff0, v1
	v_mov_b32_e32 v2, 0
	ds_write_b32 v1, v2
	s_or_b64 exec, exec, s[4:5]
	s_load_dwordx2 s[4:5], s[0:1], 0x80
	s_load_dwordx16 s[80:95], s[0:1], 0x0
	s_add_u32 s12, s78, 0xfc00000
	s_addc_u32 s13, s79, 0
	s_mov_b32 s48, 0
	s_waitcnt lgkmcnt(0)
	s_sub_i32 s4, s5, s4
	s_cmp_lt_i32 s4, 2
	v_cmp_eq_u32_e32 vcc, 0, v178
	s_barrier
	s_cbranch_scc1 .LBB0_7
	s_getreg_b32 s4, hwreg(HW_REG_XCC_ID, 0, 4)
	s_and_b32 s48, s4, 15
	s_and_saveexec_b64 s[4:5], vcc
	s_cbranch_execz .LBB0_6
	s_mov_b64 s[6:7], exec
	v_mbcnt_lo_u32_b32 v1, s6, 0
	v_mbcnt_hi_u32_b32 v1, s7, v1
	v_cmp_eq_u32_e32 vcc, 0, v1
	s_and_b64 s[8:9], exec, vcc
	s_mov_b64 exec, s[8:9]
	s_cbranch_execz .LBB0_6
	s_lshl_b32 s8, s48, 8
	s_bcnt1_i32_b64 s6, s[6:7]
	v_mov_b32_e32 v1, s8
	v_mov_b32_e32 v2, s6
	global_atomic_add v1, v2, s[12:13] offset:1024

; __global__ void __launch_bounds__(512) hymba_fwd(Args a) {
;     ...
;                 for (int u = bx; u < 512; u += G) {
;                     int bh, qb; if (G == 256) { const int v = (bx & 7) * 32 + (bx >> 3);
;                         bh = v >> 2; const int s = v & 3; qb = (u < 256) ? 7 - s : s; } else { bh = u >> 3; qb = 7 - (u & 7); }
;                     moba_unit(a, l, lds, bh >> 3, bh & 7, qb);
;                 }
;             }
;             for (int u0 = bx; u0 < 256; u0 += G) { const int u = (G == 256) ? (u0 & 7) * 32 + (u0 >> 3) : u0;
;                 mem_unit(a, l, lds, u >> 5, (u >> 3) & 3, u & 7); }
.LBB0_516:
	s_or_b64 exec, exec, s[14:15]
	v_readlane_b32 s4, v245, 47
	v_readlane_b32 s5, v245, 48
	s_andn2_b64 vcc, exec, s[4:5]
	s_mov_b32 s18, s2
	s_waitcnt lgkmcnt(0)
	s_barrier
	s_bitcmp1_b32 s101, 0
	s_cbranch_scc1 .LBB0_517
	s_cbranch_vccz .LBB0_544
.LBB0_517:
	v_readlane_b32 s4, v245, 52
	v_readlane_b32 s5, v245, 53
	s_andn2_b64 vcc, exec, s[4:5]
	s_bitcmp1_b32 s101, 1
	s_cbranch_scc1 .LBB0_522
	s_cbranch_vccnz .LBB0_522
	s_mov_b32 s43, s7
	s_lshl_b64 s[4:5], s[42:43], 2
	s_add_u32 s42, s74, s4
	s_addc_u32 s43, s75, s5
	s_add_u32 s44, s72, s4
	s_addc_u32 s45, s73, s5
	s_mov_b32 s14, s2

; __device__ __forceinline__ int otid() { int t = threadIdx.x; asm volatile("" : "+v"(t)); return t; }
; __device__ __forceinline__ void hgrn_scan_phase(const Args& a) {
;     const int id = blockIdx.x * 512 + otid(), NT = gridDim.x * 512;
;     for (int it = id; it < 32 * 128 * 32; it += NT) {
; __global__ void __launch_bounds__(512) hymba_fwd(Args a) {
;     ...
;             for (int u0 = bx; u0 < 256; u0 += G) { const int u = (G == 256) ? (u0 & 7) * 32 + (u0 >> 3) : u0;
;                 mem_unit(a, l, lds, u >> 5, (u >> 3) & 3, u & 7); }
;             hgrn_scan_phase(a);
.LBB0_522:
	s_bitcmp1_b32 s101, 2
	s_cbranch_scc0 .Lprobe_noskip_scan
	s_mov_b64 s[40:41], exec
	s_branch .LBB0_527

; #define SEAM(k) do { if (IN(k) && IN((k) + 1)) { if (a.pad == 0x5eed) cg::this_grid().sync(); xcd_barrier(xbar); } } while (0)
; __global__ void __launch_bounds__(512) hymba_fwd(Args a) {
;     ...
;         }
;         if (l == 0) SEAM(base + 4);
;     }
;     ...
; }
.LBB0_870:
	s_cmp_lg_u32 s99, 0
	s_cbranch_scc1 .Lprobe_done
	s_mov_b32 s99, 1
	s_mov_b32 s101, 3
	s_mov_b64 exec, -1
	s_waitcnt vmcnt(0) lgkmcnt(0)
	s_barrier
	v_readlane_b32 s4, v246, 2
	v_readlane_b32 s5, v246, 3
	s_sub_u32 s4, s4, 0x90
	s_subb_u32 s5, s5, 0
	s_load_dwordx2 s[6:7], s[4:5], 0x78
	s_load_dword s12, s[4:5], 0x90
	s_waitcnt lgkmcnt(0)
	s_add_u32 s8, s6, 0xfc00000
	s_addc_u32 s9, s7, 0
	v_and_b32_e32 v4, 0x3ff, v178
	v_mov_b32_e32 v1, 0
	v_cmp_eq_u32_e32 vcc, 0, v4
	s_and_saveexec_b64 s[10:11], vcc
	s_cbranch_execz .Lprobe_bar_done
	v_mov_b32_e32 v2, 1
	global_atomic_add v1, v2, s[8:9] offset:64
.Lprobe_spin:
	s_sleep 1
	global_load_dword v3, v1, s[8:9] offset:64 sc1
	s_waitcnt vmcnt(0)
	v_cmp_ne_u32_e32 vcc, s12, v3
	s_cbranch_vccnz .Lprobe_spin
.Lprobe_bar_done:
	s_or_b64 exec, exec, s[10:11]
	s_barrier
	s_lshl_b32 s13, s100, 9
	s_add_u32 s14, s6, 0xf800000
	s_addc_u32 s15, s7, 0
	s_add_u32 s14, s14, s13
	s_addc_u32 s15, s15, 0
	s_add_u32 s16, s6, 0x1e00000
	s_addc_u32 s17, s7, 0
	v_cmp_gt_u32_e32 vcc, 100, v4
	s_and_saveexec_b64 s[10:11], vcc
	s_cbranch_execz .Lprobe_copy_done
	v_lshlrev_b32_e32 v1, 2, v4
	global_load_dword v2, v1, s[4:5]
	s_waitcnt vmcnt(0)
	v_mov_b32_e32 v3, 3
	v_cmp_eq_u32_e32 vcc, 32, v4
	s_nop 1
	v_cndmask_b32_e32 v2, v2, v3, vcc
	v_mov_b32_e32 v3, 4
	v_cmp_eq_u32_e32 vcc, 33, v4
	s_nop 1
	v_cndmask_b32_e32 v2, v2, v3, vcc
	global_store_dword v1, v2, s[14:15]
	s_waitcnt vmcnt(0)
.Lprobe_copy_done:
	s_or_b64 exec, exec, s[10:11]
	s_barrier
	s_mov_b32 s0, s14
	s_mov_b32 s1, s15
	s_mov_b32 s2, s100
	v_mov_b32_e32 v0, v178
	s_branch .Lprobe_reentry

; #define LAS __attribute__((address_space(3)))
; __global__ void __launch_bounds__(512) hymba_fwd(Args a) {
;     extern __shared__ __attribute__((aligned(16))) unsigned char lds_raw[];
;     LAS unsigned char* lds = (LAS unsigned char*)lds_raw;
	.amdhsa_kernel _Z9hymba_fwd4Args
		.amdhsa_group_segment_fixed_size 0
		.amdhsa_private_segment_fixed_size 0
		.amdhsa_kernarg_size 400
		.amdhsa_user_sgpr_count 2
		.amdhsa_user_sgpr_dispatch_ptr 0
		.amdhsa_user_sgpr_queue_ptr 0
		.amdhsa_user_sgpr_kernarg_segment_ptr 1
		.amdhsa_user_sgpr_dispatch_id 0
		.amdhsa_user_sgpr_kernarg_preload_length 0
		.amdhsa_user_sgpr_kernarg_preload_offset 0
		.amdhsa_user_sgpr_private_segment_size 0
		.amdhsa_uses_dynamic_stack 0
		.amdhsa_enable_private_segment 0
		.amdhsa_system_sgpr_workgroup_id_x 1
		.amdhsa_system_sgpr_workgroup_id_y 0
		.amdhsa_system_sgpr_workgroup_id_z 0
		.amdhsa_system_sgpr_workgroup_info 0
		.amdhsa_system_vgpr_workitem_id 2
		.amdhsa_next_free_vgpr 248
		.amdhsa_next_free_sgpr 102
		.amdhsa_accum_offset 248
		.amdhsa_reserve_vcc 1
		.amdhsa_float_round_mode_32 0
		.amdhsa_float_round_mode_16_64 0
		.amdhsa_float_denorm_mode_32 3
		.amdhsa_float_denorm_mode_16_64 3
		.amdhsa_dx10_clamp 1
		.amdhsa_ieee_mode 1
		.amdhsa_fp16_overflow 0
		.amdhsa_tg_split 0
		.amdhsa_exception_fp_ieee_invalid_op 0
		.amdhsa_exception_fp_denorm_src 0
		.amdhsa_exception_fp_ieee_div_zero 0
		.amdhsa_exception_fp_ieee_overflow 0
		.amdhsa_exception_fp_ieee_underflow 0
		.amdhsa_exception_fp_ieee_inexact 0
		.amdhsa_exception_int_div_zero 0
	.end_amdhsa_kernel

amdhsa.kernels:
  - .agpr_count:     0
    .args:
      - .offset:         0
        .size:           144
        .value_kind:     by_value
      - .offset:         144
        .size:           4
        .value_kind:     hidden_block_count_x
      - .offset:         148
        .size:           4
        .value_kind:     hidden_block_count_y
      - .offset:         152
        .size:           4
        .value_kind:     hidden_block_count_z
      - .offset:         156
        .size:           2
        .value_kind:     hidden_group_size_x
      - .offset:         158
        .size:           2
        .value_kind:     hidden_group_size_y
      - .offset:         160
        .size:           2
        .value_kind:     hidden_group_size_z
      - .offset:         162
        .size:           2
        .value_kind:     hidden_remainder_x
      - .offset:         164
        .size:           2
        .value_kind:     hidden_remainder_y
      - .offset:         166
        .size:           2
        .value_kind:     hidden_remainder_z
      - .offset:         184
        .size:           8
        .value_kind:     hidden_global_offset_x
      - .offset:         192
        .size:           8
        .value_kind:     hidden_global_offset_y
      - .offset:         200
        .size:           8
        .value_kind:     hidden_global_offset_z
      - .offset:         208
        .size:           2
        .value_kind:     hidden_grid_dims
      - .offset:         232
        .size:           8
        .value_kind:     hidden_multigrid_sync_arg
      - .offset:         264
        .size:           4
        .value_kind:     hidden_dynamic_lds_size
    .group_segment_fixed_size: 0
    .kernarg_segment_align: 8
    .kernarg_segment_size: 400
    .language:       OpenCL C
    .language_version:
      - 2
      - 0
    .max_flat_workgroup_size: 512
    .name:           _Z9hymba_fwd4Args
    .private_segment_fixed_size: 0
    .sgpr_count:     108
    .sgpr_spill_count: 193
    .symbol:         _Z9hymba_fwd4Args.kd
    .uniform_work_group_size: 1
    .uses_dynamic_stack: false
    .vgpr_count:     248
    .vgpr_spill_count: 0
    .wavefront_size: 64
